# P4a QK-norm epilogue: norm weights loaded once per unit and parked (no per-group vmcnt(0) behind stores); P6 epilogue x loads run ahead; softmax-shift register no longer clobbered by G2
# speedup vs baseline: 1.0437x; 1.0025x over previous
.LBB0_563:
	v_lshlrev_b32_e32 v252, 4, v58
	s_and_b64 vcc, exec, s[6:7]
	s_cbranch_vccz .Lg2h_setup
	s_lshl_b32 s4, s83, 11
	s_add_u32 s28, s28, s4
	s_addc_u32 s29, s29, 0
	s_add_u32 s48, s92, s46
	s_addc_u32 s49, s93, s47
	s_lshl_b32 s4, s78, 3
	s_add_u32 s48, s48, s4
	s_addc_u32 s49, s49, 0
	s_add_u32 s48, s48, 0xdd20000
	s_addc_u32 s49, s49, 0
	s_add_u32 s36, s92, s36
	s_addc_u32 s37, s93, s37
	s_add_u32 s36, s36, 0x80000
	s_addc_u32 s37, s37, 0
	global_load_dword v236, v1, s[36:37]
	s_add_u32 s36, s36, 32
	s_addc_u32 s37, s37, 0
	s_mov_b32 s19, 0
	v_mov_b32_e32 v238, v252
	v_and_b32_e32 v250, 15, v58
	v_lshlrev_b32_e32 v250, 1, v250
	v_lshrrev_b32_e32 v251, 4, v58
	v_lshlrev_b32_e32 v251, 13, v251
	v_add_u32_e32 v239, v250, v251
	v_add_u32_e32 v240, 0x1000, v239
	v_add_u32_e32 v241, 0x8000, v239
	v_add_u32_e32 v242, 0x9000, v239
	v_add_u32_e32 v243, 0x10000, v239
	v_add_u32_e32 v246, 0x11000, v239
	v_add_u32_e32 v253, 0x18000, v239
	v_add_u32_e32 v248, 0x19000, v239
	v_lshlrev_b32_e32 v249, 3, v58

.Lg2c_noload:
	s_waitcnt lgkmcnt(8)
	v_mfma_f32_16x16x32_bf16 v[176:179], v[144:147], v[70:73], v[176:179]
	v_mfma_f32_16x16x32_bf16 v[196:199], v[160:163], v[70:73], v[196:199]
	v_mfma_f32_16x16x32_bf16 v[180:183], v[148:151], v[70:73], v[180:183]
	v_mfma_f32_16x16x32_bf16 v[200:203], v[164:167], v[70:73], v[200:203]
	v_mfma_f32_16x16x32_bf16 v[184:187], v[152:155], v[70:73], v[184:187]
	v_mfma_f32_16x16x32_bf16 v[204:207], v[168:171], v[70:73], v[204:207]
	v_mfma_f32_16x16x32_bf16 v[188:191], v[156:159], v[70:73], v[188:191]
	v_mfma_f32_16x16x32_bf16 v[208:211], v[172:175], v[70:73], v[208:211]
	s_waitcnt lgkmcnt(0)
	s_barrier
	ds_read_b128 v[112:115], v238 offset:32768
	ds_read_b128 v[116:119], v238 offset:34816
	ds_read_b128 v[120:123], v238 offset:36864
	ds_read_b128 v[124:127], v238 offset:38912
	ds_read_b128 v[128:131], v238 offset:40960
	ds_read_b128 v[132:135], v238 offset:43008
	ds_read_b128 v[136:139], v238 offset:45056
	ds_read_b128 v[140:143], v238 offset:47104
	v_mfma_f32_16x16x32_bf16 v[176:179], v[80:83], v[74:77], v[176:179]
	v_mfma_f32_16x16x32_bf16 v[180:183], v[84:87], v[74:77], v[180:183]
	v_mfma_f32_16x16x32_bf16 v[184:187], v[88:91], v[74:77], v[184:187]
	v_mfma_f32_16x16x32_bf16 v[188:191], v[92:95], v[74:77], v[188:191]
	v_mfma_f32_16x16x32_bf16 v[196:199], v[96:99], v[74:77], v[196:199]
	v_sub_f32_e32 v212, v212, v176
	v_sub_f32_e32 v213, v213, v177
	v_sub_f32_e32 v214, v214, v178
	v_sub_f32_e32 v215, v215, v179
	v_mfma_f32_16x16x32_bf16 v[200:203], v[100:103], v[74:77], v[200:203]
	v_sub_f32_e32 v216, v216, v180
	v_sub_f32_e32 v217, v217, v181
	v_sub_f32_e32 v218, v218, v182
	v_sub_f32_e32 v219, v219, v183
	v_mfma_f32_16x16x32_bf16 v[204:207], v[104:107], v[74:77], v[204:207]
	v_sub_f32_e32 v220, v220, v184
	v_sub_f32_e32 v221, v221, v185
	v_sub_f32_e32 v222, v222, v186
	v_sub_f32_e32 v223, v223, v187
	v_mfma_f32_16x16x32_bf16 v[208:211], v[108:111], v[74:77], v[208:211]
	v_sub_f32_e32 v224, v224, v188
	v_sub_f32_e32 v225, v225, v189
	v_sub_f32_e32 v226, v226, v190
	v_sub_f32_e32 v227, v227, v191
	ds_read_b128 v[144:147], v238 offset:33792
	ds_read_b128 v[148:151], v238 offset:35840
	ds_read_b128 v[152:155], v238 offset:37888
	ds_read_b128 v[156:159], v238 offset:39936
	ds_read_b128 v[160:163], v238 offset:41984
	ds_read_b128 v[164:167], v238 offset:44032
	ds_read_b128 v[168:171], v238 offset:46080
	ds_read_b128 v[172:175], v238 offset:48128
	v_cvt_pk_bf16_f32 v228, v212, v213
	v_cvt_pk_bf16_f32 v229, v214, v215
	v_cvt_pk_bf16_f32 v230, v216, v217
	v_cvt_pk_bf16_f32 v231, v218, v219
	v_cvt_pk_bf16_f32 v232, v220, v221
	v_cvt_pk_bf16_f32 v233, v222, v223
	v_cvt_pk_bf16_f32 v234, v224, v225
	v_cvt_pk_bf16_f32 v235, v226, v227
	s_waitcnt lgkmcnt(8)
	s_nop 1
	v_mfma_f32_16x16x32_bf16 v[4:7], v[112:115], v[228:231], v[4:7]
	v_mfma_f32_16x16x32_bf16 v[8:11], v[116:119], v[228:231], v[8:11]
	v_mfma_f32_16x16x32_bf16 v[12:15], v[120:123], v[228:231], v[12:15]
	v_mfma_f32_16x16x32_bf16 v[16:19], v[124:127], v[228:231], v[16:19]
	v_mfma_f32_16x16x32_bf16 v[20:23], v[128:131], v[228:231], v[20:23]
	v_mfma_f32_16x16x32_bf16 v[24:27], v[132:135], v[228:231], v[24:27]
	v_mfma_f32_16x16x32_bf16 v[28:31], v[136:139], v[228:231], v[28:31]
	v_mfma_f32_16x16x32_bf16 v[32:35], v[140:143], v[228:231], v[32:35]
	ds_read_b128 v[80:83], v238 offset:49152
	ds_read_b128 v[84:87], v238 offset:51200
	ds_read_b128 v[88:91], v238 offset:53248
	ds_read_b128 v[92:95], v238 offset:55296
	ds_read_b128 v[96:99], v238 offset:50176
	ds_read_b128 v[100:103], v238 offset:52224
	ds_read_b128 v[104:107], v238 offset:54272
	ds_read_b128 v[108:111], v238 offset:56320
	s_waitcnt lgkmcnt(8)
	v_mfma_f32_16x16x32_bf16 v[4:7], v[144:147], v[232:235], v[4:7]
	v_mfma_f32_16x16x32_bf16 v[8:11], v[148:151], v[232:235], v[8:11]
	v_mfma_f32_16x16x32_bf16 v[12:15], v[152:155], v[232:235], v[12:15]
	v_mfma_f32_16x16x32_bf16 v[16:19], v[156:159], v[232:235], v[16:19]
	v_mfma_f32_16x16x32_bf16 v[20:23], v[160:163], v[232:235], v[20:23]
	v_mfma_f32_16x16x32_bf16 v[24:27], v[164:167], v[232:235], v[24:27]
	v_mfma_f32_16x16x32_bf16 v[28:31], v[168:171], v[232:235], v[28:31]
	v_mfma_f32_16x16x32_bf16 v[32:35], v[172:175], v[232:235], v[32:35]
	s_waitcnt lgkmcnt(0)
	v_mfma_f32_16x16x32_bf16 v[196:199], v[80:83], v[228:231], v[196:199]
	v_mfma_f32_16x16x32_bf16 v[200:203], v[84:87], v[228:231], v[200:203]
	v_mfma_f32_16x16x32_bf16 v[204:207], v[88:91], v[228:231], v[204:207]
	v_mfma_f32_16x16x32_bf16 v[208:211], v[92:95], v[228:231], v[208:211]
	v_mfma_f32_16x16x32_bf16 v[196:199], v[96:99], v[232:235], v[196:199]
	v_mfma_f32_16x16x32_bf16 v[200:203], v[100:103], v[232:235], v[200:203]
	v_mfma_f32_16x16x32_bf16 v[204:207], v[104:107], v[232:235], v[204:207]
	v_mfma_f32_16x16x32_bf16 v[208:211], v[108:111], v[232:235], v[208:211]
	s_nop 7
	s_nop 3
	v_cvt_pk_bf16_f32 v112, v196, v197
	v_cvt_pk_bf16_f32 v113, v198, v199
	v_cvt_pk_bf16_f32 v114, v200, v201
	v_cvt_pk_bf16_f32 v115, v202, v203
	v_cvt_pk_bf16_f32 v116, v204, v205
	v_cvt_pk_bf16_f32 v117, v206, v207
	v_cvt_pk_bf16_f32 v118, v208, v209
	v_cvt_pk_bf16_f32 v119, v210, v211
	global_store_short v239, v112, s[28:29]
	global_store_short_d16_hi v239, v112, s[28:29] offset:2048
	global_store_short v240, v113, s[28:29]
	global_store_short_d16_hi v240, v113, s[28:29] offset:2048
	global_store_short v241, v114, s[28:29]
	global_store_short_d16_hi v241, v114, s[28:29] offset:2048
	global_store_short v242, v115, s[28:29]
	global_store_short_d16_hi v242, v115, s[28:29] offset:2048
	global_store_short v243, v116, s[28:29]
	global_store_short_d16_hi v243, v116, s[28:29] offset:2048
	global_store_short v246, v117, s[28:29]
	global_store_short_d16_hi v246, v117, s[28:29] offset:2048
	global_store_short v253, v118, s[28:29]
	global_store_short_d16_hi v253, v118, s[28:29] offset:2048
	global_store_short v248, v119, s[28:29]
	global_store_short_d16_hi v248, v119, s[28:29] offset:2048
	s_add_u32 s28, s28, 0x20000
	s_addc_u32 s29, s29, 0
	s_add_u32 s48, s48, 0x20000
	s_addc_u32 s49, s49, 0
	s_add_u32 s36, s36, 32
	s_addc_u32 s37, s37, 0
	v_xor_b32_e32 v238, 0xe000, v238
	s_add_i32 s19, s19, 1
	s_cmp_lt_u32 s19, 32
	s_barrier
	s_cbranch_scc1 .Lg2c_loop
	s_branch .Lg2_exit

.LBB0_656:
	s_lshl_b32 s13, 1, s11
	s_and_b32 s13, s13, 12
	s_cmp_lg_u32 s13, 0
	s_cbranch_scc0 .LBB0_662
	v_pk_mul_f32 v[148:149], v[126:127], v[126:127]
	v_pk_mul_f32 v[172:173], v[124:125], v[124:125]
	v_mul_f32_e32 v136, v104, v104
	v_pk_mov_b32 v[174:175], v[172:173], v[148:149] op_sel:[1,0]
	v_mov_b32_e32 v173, v149
	v_pk_add_f32 v[148:149], v[174:175], v[172:173]
	v_pk_mul_f32 v[172:173], v[122:123], v[122:123]
	v_pk_mul_f32 v[174:175], v[120:121], v[120:121]
	v_mul_f32_e32 v146, v105, v105
	v_pk_mov_b32 v[176:177], v[174:175], v[172:173] op_sel:[1,0]
	v_mov_b32_e32 v175, v173
	v_pk_add_f32 v[172:173], v[176:177], v[174:175]
	v_pk_add_f32 v[148:149], v[148:149], v[148:149] op_sel:[0,1] op_sel_hi:[1,0]
	v_pk_add_f32 v[172:173], v[172:173], v[172:173] op_sel:[0,1] op_sel_hi:[1,0]
	v_mov_b32_e32 v149, v136
	v_mov_b32_e32 v173, v146
	v_mul_f32_e32 v136, v109, v109
	s_cmp_eq_u32 s11, 2
	v_pk_add_f32 v[148:149], v[148:149], v[172:173]
	v_pk_fma_f32 v[172:173], v[108:109], v[108:109], v[136:137] op_sel_hi:[1,1,0]
	v_mul_f32_e32 v136, v111, v111
	s_cselect_b64 vcc, -1, 0
	v_mul_f32_e32 v171, v106, v106
	v_mul_f32_e32 v176, v107, v107
	v_pk_fma_f32 v[174:175], v[110:111], v[110:111], v[136:137] op_sel_hi:[1,1,0]
	s_and_b64 s[42:43], vcc, exec
	v_mov_b32_e32 v173, v171
	v_mov_b32_e32 v175, v176
	s_cselect_b32 s43, s91, s53
	s_cselect_b32 s42, s90, s52
	v_pk_add_f32 v[172:173], v[172:173], v[174:175]
	v_cndmask_b32_e32 v170, 1.0, v169, vcc
	v_pk_add_f32 v[148:149], v[148:149], v[172:173]
	global_load_dwordx4 v[172:175], v167, s[42:43] offset:16
	global_load_dwordx4 v[176:179], v167, s[42:43]
	v_add_f32_e32 v136, v148, v149
	ds_bpermute_b32 v146, v153, v136
	s_lshl_b32 s11, s8, 8
	v_add_u32_e32 v148, s11, v150
	s_lshl_b32 s13, s9, 2
	v_ashrrev_i32_e32 v149, 31, v148
	s_waitcnt lgkmcnt(0)
	v_add_f32_e32 v136, v136, v146
	ds_bpermute_b32 v146, v154, v136
	s_and_b32 s13, s13, 12
	v_lshlrev_b64 v[148:149], 11, v[148:149]
	s_or_b32 s13, s13, s49
	v_lshl_add_u64 v[148:149], s[36:37], 0, v[148:149]
	s_waitcnt lgkmcnt(0)
	v_add_f32_e32 v136, v136, v146
	v_fmamk_f32 v136, v136, 0x3c800000, v168
	v_rsq_f32_e32 v136, v136
	v_mul_f32_e32 v171, v89, v89
	v_mul_f32_e32 v146, v170, v136
	v_pk_mul_f32 v[180:181], v[124:125], v[146:147] op_sel_hi:[1,0]
	v_pk_mul_f32 v[182:183], v[126:127], v[146:147] op_sel_hi:[1,0]
	v_lshl_or_b32 v136, s13, 7, v151
	v_lshl_add_u64 v[148:149], v[148:149], 0, v[136:137]
	s_waitcnt vmcnt(0)
	v_mov_b64_e32 v[252:253], v[172:173]
	v_mov_b64_e32 v[254:255], v[174:175]
	v_mov_b64_e32 v[248:249], v[176:177]
	v_mov_b64_e32 v[250:251], v[178:179]
	v_pk_mul_f32 v[178:179], v[178:179], v[182:183]
	v_pk_mul_f32 v[176:177], v[176:177], v[180:181]
	v_pk_mul_f32 v[180:181], v[120:121], v[146:147] op_sel_hi:[1,0]
	v_pk_mul_f32 v[182:183], v[122:123], v[146:147] op_sel_hi:[1,0]
	s_nop 0
	v_pk_mul_f32 v[182:183], v[174:175], v[182:183]
	v_pk_mul_f32 v[174:175], v[172:173], v[180:181]
	v_cvt_pk_bf16_f32 v172, v176, v177
	v_cvt_pk_bf16_f32 v173, v178, v179
	v_cvt_pk_bf16_f32 v174, v174, v175
	v_cvt_pk_bf16_f32 v175, v182, v183
	global_store_dwordx4 v[148:149], v[172:175], off
	global_load_dwordx4 v[172:175], v167, s[42:43] offset:144
	s_nop 0
	global_load_dwordx4 v[176:179], v167, s[42:43] offset:128
	v_pk_mul_f32 v[180:181], v[108:109], v[146:147] op_sel_hi:[1,0]
	v_pk_mul_f32 v[182:183], v[110:111], v[146:147] op_sel_hi:[1,0]
	s_waitcnt vmcnt(0)
	v_mov_b64_e32 v[124:125], v[172:173]
	v_mov_b64_e32 v[126:127], v[174:175]
	v_mov_b64_e32 v[120:121], v[176:177]
	v_mov_b64_e32 v[122:123], v[178:179]
	v_pk_mul_f32 v[176:177], v[176:177], v[180:181]
	v_pk_mul_f32 v[178:179], v[178:179], v[182:183]
	v_pk_mul_f32 v[180:181], v[104:105], v[146:147] op_sel_hi:[1,0]
	v_pk_mul_f32 v[182:183], v[106:107], v[146:147] op_sel_hi:[1,0]
	v_mul_f32_e32 v146, v88, v88
	v_pk_mul_f32 v[182:183], v[174:175], v[182:183]
	v_pk_mul_f32 v[174:175], v[172:173], v[180:181]
	v_cvt_pk_bf16_f32 v172, v176, v177
	v_cvt_pk_bf16_f32 v173, v178, v179
	v_cvt_pk_bf16_f32 v174, v174, v175
	v_cvt_pk_bf16_f32 v175, v182, v183
	global_store_dwordx4 v[148:149], v[172:175], off offset:64
	v_pk_mul_f32 v[148:149], v[118:119], v[118:119]
	s_nop 0
	v_pk_mul_f32 v[172:173], v[116:117], v[116:117]
	s_nop 0
	v_pk_mov_b32 v[174:175], v[172:173], v[148:149] op_sel:[1,0]
	v_mov_b32_e32 v173, v149
	v_pk_add_f32 v[148:149], v[174:175], v[172:173]
	v_pk_mul_f32 v[172:173], v[114:115], v[114:115]
	v_pk_mul_f32 v[174:175], v[112:113], v[112:113]
	v_pk_add_f32 v[148:149], v[148:149], v[148:149] op_sel:[0,1] op_sel_hi:[1,0]
	v_pk_mov_b32 v[176:177], v[174:175], v[172:173] op_sel:[1,0]
	v_mov_b32_e32 v175, v173
	v_pk_add_f32 v[172:173], v[176:177], v[174:175]
	v_mov_b32_e32 v149, v146
	v_pk_add_f32 v[172:173], v[172:173], v[172:173] op_sel:[0,1] op_sel_hi:[1,0]
	v_mul_f32_e32 v146, v93, v93
	v_mov_b32_e32 v173, v171
	v_mul_f32_e32 v174, v90, v90
	v_pk_add_f32 v[148:149], v[148:149], v[172:173]
	v_pk_fma_f32 v[172:173], v[92:93], v[92:93], v[146:147] op_sel_hi:[1,1,0]
	v_mul_f32_e32 v146, v95, v95
	v_mul_f32_e32 v176, v91, v91
	v_mov_b32_e32 v173, v174
	v_pk_fma_f32 v[174:175], v[94:95], v[94:95], v[146:147] op_sel_hi:[1,1,0]
	v_mul_f32_e32 v171, v73, v73
	v_mov_b32_e32 v175, v176
	v_pk_add_f32 v[172:173], v[172:173], v[174:175]
	s_nop 0
	v_pk_add_f32 v[148:149], v[148:149], v[172:173]
	s_nop 1
	v_mov_b64_e32 v[172:173], v[252:253]
	v_mov_b64_e32 v[174:175], v[254:255]
	v_mov_b64_e32 v[176:177], v[248:249]
	v_mov_b64_e32 v[178:179], v[250:251]
	v_add_f32_e32 v146, v148, v149
	ds_bpermute_b32 v149, v153, v146
	v_add_u32_e32 v148, s11, v155
	s_waitcnt lgkmcnt(0)
	v_add_f32_e32 v146, v146, v149
	ds_bpermute_b32 v149, v154, v146
	s_waitcnt lgkmcnt(0)
	v_add_f32_e32 v146, v146, v149
	v_fmamk_f32 v146, v146, 0x3c800000, v168
	v_rsq_f32_e32 v146, v146
	v_ashrrev_i32_e32 v149, 31, v148
	v_lshlrev_b64 v[148:149], 11, v[148:149]
	v_lshl_add_u64 v[148:149], s[36:37], 0, v[148:149]
	v_mul_f32_e32 v146, v170, v146
	v_pk_mul_f32 v[180:181], v[116:117], v[146:147] op_sel_hi:[1,0]
	v_pk_mul_f32 v[182:183], v[118:119], v[146:147] op_sel_hi:[1,0]
	v_lshl_add_u64 v[148:149], v[148:149], 0, v[136:137]
	v_pk_mul_f32 v[178:179], v[178:179], v[182:183]
	v_pk_mul_f32 v[176:177], v[176:177], v[180:181]
	v_pk_mul_f32 v[180:181], v[112:113], v[146:147] op_sel_hi:[1,0]
	v_pk_mul_f32 v[182:183], v[114:115], v[146:147] op_sel_hi:[1,0]
	s_nop 0
	v_pk_mul_f32 v[182:183], v[174:175], v[182:183]
	v_pk_mul_f32 v[174:175], v[172:173], v[180:181]
	v_cvt_pk_bf16_f32 v172, v176, v177
	v_cvt_pk_bf16_f32 v173, v178, v179
	v_cvt_pk_bf16_f32 v174, v174, v175
	v_cvt_pk_bf16_f32 v175, v182, v183
	global_store_dwordx4 v[148:149], v[172:175], off
	s_nop 1
	v_mov_b64_e32 v[172:173], v[124:125]
	v_mov_b64_e32 v[174:175], v[126:127]
	s_nop 0
	v_mov_b64_e32 v[176:177], v[120:121]
	v_mov_b64_e32 v[178:179], v[122:123]
	v_pk_mul_f32 v[180:181], v[92:93], v[146:147] op_sel_hi:[1,0]
	v_pk_mul_f32 v[182:183], v[94:95], v[146:147] op_sel_hi:[1,0]
	v_pk_mul_f32 v[176:177], v[176:177], v[180:181]
	v_pk_mul_f32 v[178:179], v[178:179], v[182:183]
	v_pk_mul_f32 v[180:181], v[88:89], v[146:147] op_sel_hi:[1,0]
	v_pk_mul_f32 v[182:183], v[90:91], v[146:147] op_sel_hi:[1,0]
	v_mul_f32_e32 v146, v72, v72
	v_pk_mul_f32 v[182:183], v[174:175], v[182:183]
	v_pk_mul_f32 v[174:175], v[172:173], v[180:181]
	v_cvt_pk_bf16_f32 v172, v176, v177
	v_cvt_pk_bf16_f32 v173, v178, v179
	v_cvt_pk_bf16_f32 v174, v174, v175
	v_cvt_pk_bf16_f32 v175, v182, v183
	global_store_dwordx4 v[148:149], v[172:175], off offset:64
	v_pk_mul_f32 v[148:149], v[102:103], v[102:103]
	s_nop 0
	v_pk_mul_f32 v[172:173], v[100:101], v[100:101]
	s_nop 0
	v_pk_mov_b32 v[174:175], v[172:173], v[148:149] op_sel:[1,0]
	v_mov_b32_e32 v173, v149
	v_pk_add_f32 v[148:149], v[174:175], v[172:173]
	v_pk_mul_f32 v[172:173], v[98:99], v[98:99]
	v_pk_mul_f32 v[174:175], v[96:97], v[96:97]
	v_pk_add_f32 v[148:149], v[148:149], v[148:149] op_sel:[0,1] op_sel_hi:[1,0]
	v_pk_mov_b32 v[176:177], v[174:175], v[172:173] op_sel:[1,0]
	v_mov_b32_e32 v175, v173
	v_pk_add_f32 v[172:173], v[176:177], v[174:175]
	v_mov_b32_e32 v149, v146
	v_pk_add_f32 v[172:173], v[172:173], v[172:173] op_sel:[0,1] op_sel_hi:[1,0]
	v_mul_f32_e32 v146, v77, v77
	v_mov_b32_e32 v173, v171
	v_mul_f32_e32 v174, v74, v74
	v_pk_add_f32 v[148:149], v[148:149], v[172:173]
	v_pk_fma_f32 v[172:173], v[76:77], v[76:77], v[146:147] op_sel_hi:[1,1,0]
	v_mul_f32_e32 v146, v79, v79
	v_mul_f32_e32 v176, v75, v75
	v_mov_b32_e32 v173, v174
	v_pk_fma_f32 v[174:175], v[78:79], v[78:79], v[146:147] op_sel_hi:[1,1,0]
	v_mul_f32_e32 v171, v65, v65
	v_mov_b32_e32 v175, v176
	v_pk_add_f32 v[172:173], v[172:173], v[174:175]
	s_nop 0
	v_pk_add_f32 v[148:149], v[148:149], v[172:173]
	s_nop 1
	v_mov_b64_e32 v[172:173], v[252:253]
	v_mov_b64_e32 v[174:175], v[254:255]
	v_mov_b64_e32 v[176:177], v[248:249]
	v_mov_b64_e32 v[178:179], v[250:251]
	v_add_f32_e32 v146, v148, v149
	ds_bpermute_b32 v149, v153, v146
	v_add_u32_e32 v148, s11, v156
	s_waitcnt lgkmcnt(0)
	v_add_f32_e32 v146, v146, v149
	ds_bpermute_b32 v149, v154, v146
	s_waitcnt lgkmcnt(0)
	v_add_f32_e32 v146, v146, v149
	v_fmamk_f32 v146, v146, 0x3c800000, v168
	v_rsq_f32_e32 v146, v146
	v_ashrrev_i32_e32 v149, 31, v148
	v_lshlrev_b64 v[148:149], 11, v[148:149]
	v_lshl_add_u64 v[148:149], s[36:37], 0, v[148:149]
	v_mul_f32_e32 v146, v170, v146
	v_pk_mul_f32 v[180:181], v[100:101], v[146:147] op_sel_hi:[1,0]
	v_pk_mul_f32 v[182:183], v[102:103], v[146:147] op_sel_hi:[1,0]
	v_lshl_add_u64 v[148:149], v[148:149], 0, v[136:137]
	v_pk_mul_f32 v[178:179], v[178:179], v[182:183]
	v_pk_mul_f32 v[176:177], v[176:177], v[180:181]
	v_pk_mul_f32 v[180:181], v[96:97], v[146:147] op_sel_hi:[1,0]
	v_pk_mul_f32 v[182:183], v[98:99], v[146:147] op_sel_hi:[1,0]
	s_nop 0
	v_pk_mul_f32 v[182:183], v[174:175], v[182:183]
	v_pk_mul_f32 v[174:175], v[172:173], v[180:181]
	v_cvt_pk_bf16_f32 v172, v176, v177
	v_cvt_pk_bf16_f32 v173, v178, v179
	v_cvt_pk_bf16_f32 v174, v174, v175
	v_cvt_pk_bf16_f32 v175, v182, v183
	global_store_dwordx4 v[148:149], v[172:175], off
	s_nop 1
	v_mov_b64_e32 v[172:173], v[124:125]
	v_mov_b64_e32 v[174:175], v[126:127]
	s_nop 0
	v_mov_b64_e32 v[176:177], v[120:121]
	v_mov_b64_e32 v[178:179], v[122:123]
	v_pk_mul_f32 v[180:181], v[76:77], v[146:147] op_sel_hi:[1,0]
	v_pk_mul_f32 v[182:183], v[78:79], v[146:147] op_sel_hi:[1,0]
	v_pk_mul_f32 v[176:177], v[176:177], v[180:181]
	v_pk_mul_f32 v[178:179], v[178:179], v[182:183]
	v_pk_mul_f32 v[180:181], v[72:73], v[146:147] op_sel_hi:[1,0]
	v_pk_mul_f32 v[182:183], v[74:75], v[146:147] op_sel_hi:[1,0]
	v_mul_f32_e32 v146, v64, v64
	v_pk_mul_f32 v[182:183], v[174:175], v[182:183]
	v_pk_mul_f32 v[174:175], v[172:173], v[180:181]
	v_cvt_pk_bf16_f32 v172, v176, v177
	v_cvt_pk_bf16_f32 v173, v178, v179
	v_cvt_pk_bf16_f32 v174, v174, v175
	v_cvt_pk_bf16_f32 v175, v182, v183
	global_store_dwordx4 v[148:149], v[172:175], off offset:64
	v_pk_mul_f32 v[148:149], v[86:87], v[86:87]
	s_nop 0
	v_pk_mul_f32 v[172:173], v[84:85], v[84:85]
	s_nop 0
	v_pk_mov_b32 v[174:175], v[172:173], v[148:149] op_sel:[1,0]
	v_mov_b32_e32 v173, v149
	v_pk_add_f32 v[148:149], v[174:175], v[172:173]
	v_pk_mul_f32 v[172:173], v[82:83], v[82:83]
	v_pk_mul_f32 v[174:175], v[80:81], v[80:81]
	v_pk_add_f32 v[148:149], v[148:149], v[148:149] op_sel:[0,1] op_sel_hi:[1,0]
	v_pk_mov_b32 v[176:177], v[174:175], v[172:173] op_sel:[1,0]
	v_mov_b32_e32 v175, v173
	v_pk_add_f32 v[172:173], v[176:177], v[174:175]
	v_mov_b32_e32 v149, v146
	v_pk_add_f32 v[172:173], v[172:173], v[172:173] op_sel:[0,1] op_sel_hi:[1,0]
	v_mul_f32_e32 v146, v69, v69
	v_mov_b32_e32 v173, v171
	v_mul_f32_e32 v174, v66, v66
	v_pk_add_f32 v[148:149], v[148:149], v[172:173]
	v_pk_fma_f32 v[172:173], v[68:69], v[68:69], v[146:147] op_sel_hi:[1,1,0]
	v_mul_f32_e32 v146, v71, v71
	v_mul_f32_e32 v176, v67, v67
	v_mov_b32_e32 v173, v174
	v_pk_fma_f32 v[174:175], v[70:71], v[70:71], v[146:147] op_sel_hi:[1,1,0]
	v_mul_f32_e32 v171, v41, v41
	v_mov_b32_e32 v175, v176
	v_pk_add_f32 v[172:173], v[172:173], v[174:175]
	s_nop 0
	v_pk_add_f32 v[148:149], v[148:149], v[172:173]
	s_nop 1
	v_mov_b64_e32 v[172:173], v[252:253]
	v_mov_b64_e32 v[174:175], v[254:255]
	v_mov_b64_e32 v[176:177], v[248:249]
	v_mov_b64_e32 v[178:179], v[250:251]
	v_add_f32_e32 v146, v148, v149
	ds_bpermute_b32 v149, v153, v146
	v_add_u32_e32 v148, s11, v157
	s_waitcnt lgkmcnt(0)
	v_add_f32_e32 v146, v146, v149
	ds_bpermute_b32 v149, v154, v146
	s_waitcnt lgkmcnt(0)
	v_add_f32_e32 v146, v146, v149
	v_fmamk_f32 v146, v146, 0x3c800000, v168
	v_rsq_f32_e32 v146, v146
	v_ashrrev_i32_e32 v149, 31, v148
	v_lshlrev_b64 v[148:149], 11, v[148:149]
	v_lshl_add_u64 v[148:149], s[36:37], 0, v[148:149]
	v_mul_f32_e32 v146, v170, v146
	v_pk_mul_f32 v[180:181], v[84:85], v[146:147] op_sel_hi:[1,0]
	v_pk_mul_f32 v[182:183], v[86:87], v[146:147] op_sel_hi:[1,0]
	v_lshl_add_u64 v[148:149], v[148:149], 0, v[136:137]
	v_pk_mul_f32 v[178:179], v[178:179], v[182:183]
	v_pk_mul_f32 v[176:177], v[176:177], v[180:181]
	v_pk_mul_f32 v[180:181], v[80:81], v[146:147] op_sel_hi:[1,0]
	v_pk_mul_f32 v[182:183], v[82:83], v[146:147] op_sel_hi:[1,0]
	s_nop 0
	v_pk_mul_f32 v[182:183], v[174:175], v[182:183]
	v_pk_mul_f32 v[174:175], v[172:173], v[180:181]
	v_cvt_pk_bf16_f32 v172, v176, v177
	v_cvt_pk_bf16_f32 v173, v178, v179
	v_cvt_pk_bf16_f32 v174, v174, v175
	v_cvt_pk_bf16_f32 v175, v182, v183
	global_store_dwordx4 v[148:149], v[172:175], off
	s_nop 1
	v_mov_b64_e32 v[172:173], v[124:125]
	v_mov_b64_e32 v[174:175], v[126:127]
	s_nop 0
	v_mov_b64_e32 v[176:177], v[120:121]
	v_mov_b64_e32 v[178:179], v[122:123]
	v_pk_mul_f32 v[180:181], v[68:69], v[146:147] op_sel_hi:[1,0]
	v_pk_mul_f32 v[182:183], v[70:71], v[146:147] op_sel_hi:[1,0]
	v_pk_mul_f32 v[176:177], v[176:177], v[180:181]
	v_pk_mul_f32 v[178:179], v[178:179], v[182:183]
	v_pk_mul_f32 v[180:181], v[64:65], v[146:147] op_sel_hi:[1,0]
	v_pk_mul_f32 v[182:183], v[66:67], v[146:147] op_sel_hi:[1,0]
	v_mul_f32_e32 v146, v40, v40
	v_pk_mul_f32 v[182:183], v[174:175], v[182:183]
	v_pk_mul_f32 v[174:175], v[172:173], v[180:181]
	v_cvt_pk_bf16_f32 v172, v176, v177
	v_cvt_pk_bf16_f32 v173, v178, v179
	v_cvt_pk_bf16_f32 v174, v174, v175
	v_cvt_pk_bf16_f32 v175, v182, v183
	global_store_dwordx4 v[148:149], v[172:175], off offset:64
	v_pk_mul_f32 v[148:149], v[62:63], v[62:63]
	s_nop 0
	v_pk_mul_f32 v[172:173], v[60:61], v[60:61]
	s_nop 0
	v_pk_mov_b32 v[174:175], v[172:173], v[148:149] op_sel:[1,0]
	v_mov_b32_e32 v173, v149
	v_pk_add_f32 v[148:149], v[174:175], v[172:173]
	v_pk_mul_f32 v[172:173], v[58:59], v[58:59]
	v_pk_mul_f32 v[174:175], v[56:57], v[56:57]
	v_pk_add_f32 v[148:149], v[148:149], v[148:149] op_sel:[0,1] op_sel_hi:[1,0]
	v_pk_mov_b32 v[176:177], v[174:175], v[172:173] op_sel:[1,0]
	v_mov_b32_e32 v175, v173
	v_pk_add_f32 v[172:173], v[176:177], v[174:175]
	v_mov_b32_e32 v149, v146
	v_pk_add_f32 v[172:173], v[172:173], v[172:173] op_sel:[0,1] op_sel_hi:[1,0]
	v_mul_f32_e32 v146, v45, v45
	v_mov_b32_e32 v173, v171
	v_mul_f32_e32 v174, v42, v42
	v_pk_add_f32 v[148:149], v[148:149], v[172:173]
	v_pk_fma_f32 v[172:173], v[44:45], v[44:45], v[146:147] op_sel_hi:[1,1,0]
	v_mul_f32_e32 v146, v47, v47
	v_mul_f32_e32 v176, v43, v43
	v_mov_b32_e32 v173, v174
	v_pk_fma_f32 v[174:175], v[46:47], v[46:47], v[146:147] op_sel_hi:[1,1,0]
	v_mul_f32_e32 v171, v25, v25
	v_mov_b32_e32 v175, v176
	v_pk_add_f32 v[172:173], v[172:173], v[174:175]
	s_nop 0
	v_pk_add_f32 v[148:149], v[148:149], v[172:173]
	s_nop 1
	v_mov_b64_e32 v[172:173], v[252:253]
	v_mov_b64_e32 v[174:175], v[254:255]
	v_mov_b64_e32 v[176:177], v[248:249]
	v_mov_b64_e32 v[178:179], v[250:251]
	v_add_f32_e32 v146, v148, v149
	ds_bpermute_b32 v149, v153, v146
	v_add_u32_e32 v148, s11, v158
	s_waitcnt lgkmcnt(0)
	v_add_f32_e32 v146, v146, v149
	ds_bpermute_b32 v149, v154, v146
	s_waitcnt lgkmcnt(0)
	v_add_f32_e32 v146, v146, v149
	v_fmamk_f32 v146, v146, 0x3c800000, v168
	v_rsq_f32_e32 v146, v146
	v_ashrrev_i32_e32 v149, 31, v148
	v_lshlrev_b64 v[148:149], 11, v[148:149]
	v_lshl_add_u64 v[148:149], s[36:37], 0, v[148:149]
	v_mul_f32_e32 v146, v170, v146
	v_pk_mul_f32 v[180:181], v[60:61], v[146:147] op_sel_hi:[1,0]
	v_pk_mul_f32 v[182:183], v[62:63], v[146:147] op_sel_hi:[1,0]
	v_lshl_add_u64 v[148:149], v[148:149], 0, v[136:137]
	v_pk_mul_f32 v[178:179], v[178:179], v[182:183]
	v_pk_mul_f32 v[176:177], v[176:177], v[180:181]
	v_pk_mul_f32 v[180:181], v[56:57], v[146:147] op_sel_hi:[1,0]
	v_pk_mul_f32 v[182:183], v[58:59], v[146:147] op_sel_hi:[1,0]
	s_nop 0
	v_pk_mul_f32 v[182:183], v[174:175], v[182:183]
	v_pk_mul_f32 v[174:175], v[172:173], v[180:181]
	v_cvt_pk_bf16_f32 v172, v176, v177
	v_cvt_pk_bf16_f32 v173, v178, v179
	v_cvt_pk_bf16_f32 v174, v174, v175
	v_cvt_pk_bf16_f32 v175, v182, v183
	global_store_dwordx4 v[148:149], v[172:175], off
	s_nop 1
	v_mov_b64_e32 v[172:173], v[124:125]
	v_mov_b64_e32 v[174:175], v[126:127]
	s_nop 0
	v_mov_b64_e32 v[176:177], v[120:121]
	v_mov_b64_e32 v[178:179], v[122:123]
	v_pk_mul_f32 v[180:181], v[44:45], v[146:147] op_sel_hi:[1,0]
	v_pk_mul_f32 v[182:183], v[46:47], v[146:147] op_sel_hi:[1,0]
	v_pk_mul_f32 v[176:177], v[176:177], v[180:181]
	v_pk_mul_f32 v[178:179], v[178:179], v[182:183]
	v_pk_mul_f32 v[180:181], v[40:41], v[146:147] op_sel_hi:[1,0]
	v_pk_mul_f32 v[182:183], v[42:43], v[146:147] op_sel_hi:[1,0]
	v_mul_f32_e32 v146, v24, v24
	v_pk_mul_f32 v[182:183], v[174:175], v[182:183]
	v_pk_mul_f32 v[174:175], v[172:173], v[180:181]
	v_cvt_pk_bf16_f32 v172, v176, v177
	v_cvt_pk_bf16_f32 v173, v178, v179
	v_cvt_pk_bf16_f32 v174, v174, v175
	v_cvt_pk_bf16_f32 v175, v182, v183
	global_store_dwordx4 v[148:149], v[172:175], off offset:64
	v_pk_mul_f32 v[148:149], v[54:55], v[54:55]
	s_nop 0
	v_pk_mul_f32 v[172:173], v[52:53], v[52:53]
	s_nop 0
	v_pk_mov_b32 v[174:175], v[172:173], v[148:149] op_sel:[1,0]
	v_mov_b32_e32 v173, v149
	v_pk_add_f32 v[148:149], v[174:175], v[172:173]
	v_pk_mul_f32 v[172:173], v[50:51], v[50:51]
	v_pk_mul_f32 v[174:175], v[48:49], v[48:49]
	v_pk_add_f32 v[148:149], v[148:149], v[148:149] op_sel:[0,1] op_sel_hi:[1,0]
	v_pk_mov_b32 v[176:177], v[174:175], v[172:173] op_sel:[1,0]
	v_mov_b32_e32 v175, v173
	v_pk_add_f32 v[172:173], v[176:177], v[174:175]
	v_mov_b32_e32 v149, v146
	v_pk_add_f32 v[172:173], v[172:173], v[172:173] op_sel:[0,1] op_sel_hi:[1,0]
	v_mul_f32_e32 v146, v29, v29
	v_mov_b32_e32 v173, v171
	v_mul_f32_e32 v174, v26, v26
	v_pk_add_f32 v[148:149], v[148:149], v[172:173]
	v_pk_fma_f32 v[172:173], v[28:29], v[28:29], v[146:147] op_sel_hi:[1,1,0]
	v_mul_f32_e32 v146, v31, v31
	v_mul_f32_e32 v176, v27, v27
	v_mov_b32_e32 v173, v174
	v_pk_fma_f32 v[174:175], v[30:31], v[30:31], v[146:147] op_sel_hi:[1,1,0]
	v_mul_f32_e32 v171, v9, v9
	v_mov_b32_e32 v175, v176
	v_pk_add_f32 v[172:173], v[172:173], v[174:175]
	s_nop 0
	v_pk_add_f32 v[148:149], v[148:149], v[172:173]
	s_nop 1
	v_mov_b64_e32 v[172:173], v[252:253]
	v_mov_b64_e32 v[174:175], v[254:255]
	v_mov_b64_e32 v[176:177], v[248:249]
	v_mov_b64_e32 v[178:179], v[250:251]
	v_add_f32_e32 v146, v148, v149
	ds_bpermute_b32 v149, v153, v146
	v_add_u32_e32 v148, s11, v159
	s_waitcnt lgkmcnt(0)
	v_add_f32_e32 v146, v146, v149
	ds_bpermute_b32 v149, v154, v146
	s_waitcnt lgkmcnt(0)
	v_add_f32_e32 v146, v146, v149
	v_fmamk_f32 v146, v146, 0x3c800000, v168
	v_rsq_f32_e32 v146, v146
	v_ashrrev_i32_e32 v149, 31, v148
	v_lshlrev_b64 v[148:149], 11, v[148:149]
	v_lshl_add_u64 v[148:149], s[36:37], 0, v[148:149]
	v_mul_f32_e32 v146, v170, v146
	v_pk_mul_f32 v[180:181], v[52:53], v[146:147] op_sel_hi:[1,0]
	v_pk_mul_f32 v[182:183], v[54:55], v[146:147] op_sel_hi:[1,0]
	v_lshl_add_u64 v[148:149], v[148:149], 0, v[136:137]
	v_pk_mul_f32 v[178:179], v[178:179], v[182:183]
	v_pk_mul_f32 v[176:177], v[176:177], v[180:181]
	v_pk_mul_f32 v[180:181], v[48:49], v[146:147] op_sel_hi:[1,0]
	v_pk_mul_f32 v[182:183], v[50:51], v[146:147] op_sel_hi:[1,0]
	s_nop 0
	v_pk_mul_f32 v[182:183], v[174:175], v[182:183]
	v_pk_mul_f32 v[174:175], v[172:173], v[180:181]
	v_cvt_pk_bf16_f32 v172, v176, v177
	v_cvt_pk_bf16_f32 v173, v178, v179
	v_cvt_pk_bf16_f32 v174, v174, v175
	v_cvt_pk_bf16_f32 v175, v182, v183
	global_store_dwordx4 v[148:149], v[172:175], off
	s_nop 1
	v_mov_b64_e32 v[172:173], v[124:125]
	v_mov_b64_e32 v[174:175], v[126:127]
	s_nop 0
	v_mov_b64_e32 v[176:177], v[120:121]
	v_mov_b64_e32 v[178:179], v[122:123]
	v_pk_mul_f32 v[180:181], v[28:29], v[146:147] op_sel_hi:[1,0]
	v_pk_mul_f32 v[182:183], v[30:31], v[146:147] op_sel_hi:[1,0]
	v_pk_mul_f32 v[176:177], v[176:177], v[180:181]
	v_pk_mul_f32 v[178:179], v[178:179], v[182:183]
	v_pk_mul_f32 v[180:181], v[24:25], v[146:147] op_sel_hi:[1,0]
	v_pk_mul_f32 v[182:183], v[26:27], v[146:147] op_sel_hi:[1,0]
	v_mul_f32_e32 v146, v8, v8
	v_pk_mul_f32 v[182:183], v[174:175], v[182:183]
	v_pk_mul_f32 v[174:175], v[172:173], v[180:181]
	v_cvt_pk_bf16_f32 v172, v176, v177
	v_cvt_pk_bf16_f32 v173, v178, v179
	v_cvt_pk_bf16_f32 v174, v174, v175
	v_cvt_pk_bf16_f32 v175, v182, v183
	global_store_dwordx4 v[148:149], v[172:175], off offset:64
	v_pk_mul_f32 v[148:149], v[38:39], v[38:39]
	s_nop 0
	v_pk_mul_f32 v[172:173], v[36:37], v[36:37]
	s_nop 0
	v_pk_mov_b32 v[174:175], v[172:173], v[148:149] op_sel:[1,0]
	v_mov_b32_e32 v173, v149
	v_pk_add_f32 v[148:149], v[174:175], v[172:173]
	v_pk_mul_f32 v[172:173], v[34:35], v[34:35]
	v_pk_mul_f32 v[174:175], v[32:33], v[32:33]
	v_pk_add_f32 v[148:149], v[148:149], v[148:149] op_sel:[0,1] op_sel_hi:[1,0]
	v_pk_mov_b32 v[176:177], v[174:175], v[172:173] op_sel:[1,0]
	v_mov_b32_e32 v175, v173
	v_pk_add_f32 v[172:173], v[176:177], v[174:175]
	v_mov_b32_e32 v149, v146
	v_pk_add_f32 v[172:173], v[172:173], v[172:173] op_sel:[0,1] op_sel_hi:[1,0]
	v_mul_f32_e32 v146, v13, v13
	v_mov_b32_e32 v173, v171
	v_mul_f32_e32 v174, v10, v10
	v_pk_add_f32 v[148:149], v[148:149], v[172:173]
	v_pk_fma_f32 v[172:173], v[12:13], v[12:13], v[146:147] op_sel_hi:[1,1,0]
	v_mul_f32_e32 v146, v15, v15
	v_mul_f32_e32 v176, v11, v11
	v_mov_b32_e32 v173, v174
	v_pk_fma_f32 v[174:175], v[14:15], v[14:15], v[146:147] op_sel_hi:[1,1,0]
	v_mul_f32_e32 v171, v1, v1
	v_mov_b32_e32 v175, v176
	v_pk_add_f32 v[172:173], v[172:173], v[174:175]
	s_nop 0
	v_pk_add_f32 v[148:149], v[148:149], v[172:173]
	s_nop 1
	v_mov_b64_e32 v[172:173], v[252:253]
	v_mov_b64_e32 v[174:175], v[254:255]
	v_mov_b64_e32 v[176:177], v[248:249]
	v_mov_b64_e32 v[178:179], v[250:251]
	v_add_f32_e32 v146, v148, v149
	ds_bpermute_b32 v149, v153, v146
	v_add_u32_e32 v148, s11, v160
	s_waitcnt lgkmcnt(0)
	v_add_f32_e32 v146, v146, v149
	ds_bpermute_b32 v149, v154, v146
	s_waitcnt lgkmcnt(0)
	v_add_f32_e32 v146, v146, v149
	v_fmamk_f32 v146, v146, 0x3c800000, v168
	v_rsq_f32_e32 v146, v146
	v_ashrrev_i32_e32 v149, 31, v148
	v_lshlrev_b64 v[148:149], 11, v[148:149]
	v_lshl_add_u64 v[148:149], s[36:37], 0, v[148:149]
	v_mul_f32_e32 v146, v170, v146
	v_pk_mul_f32 v[180:181], v[36:37], v[146:147] op_sel_hi:[1,0]
	v_pk_mul_f32 v[182:183], v[38:39], v[146:147] op_sel_hi:[1,0]
	v_lshl_add_u64 v[148:149], v[148:149], 0, v[136:137]
	v_pk_mul_f32 v[178:179], v[178:179], v[182:183]
	v_pk_mul_f32 v[176:177], v[176:177], v[180:181]
	v_pk_mul_f32 v[180:181], v[32:33], v[146:147] op_sel_hi:[1,0]
	v_pk_mul_f32 v[182:183], v[34:35], v[146:147] op_sel_hi:[1,0]
	s_nop 0
	v_pk_mul_f32 v[182:183], v[174:175], v[182:183]
	v_pk_mul_f32 v[174:175], v[172:173], v[180:181]
	v_cvt_pk_bf16_f32 v172, v176, v177
	v_cvt_pk_bf16_f32 v173, v178, v179
	v_cvt_pk_bf16_f32 v174, v174, v175
	v_cvt_pk_bf16_f32 v175, v182, v183
	global_store_dwordx4 v[148:149], v[172:175], off
	s_nop 1
	v_mov_b64_e32 v[172:173], v[124:125]
	v_mov_b64_e32 v[174:175], v[126:127]
	s_nop 0
	v_mov_b64_e32 v[176:177], v[120:121]
	v_mov_b64_e32 v[178:179], v[122:123]
	v_pk_mul_f32 v[180:181], v[12:13], v[146:147] op_sel_hi:[1,0]
	v_pk_mul_f32 v[182:183], v[14:15], v[146:147] op_sel_hi:[1,0]
	v_pk_mul_f32 v[176:177], v[176:177], v[180:181]
	v_pk_mul_f32 v[178:179], v[178:179], v[182:183]
	v_pk_mul_f32 v[180:181], v[8:9], v[146:147] op_sel_hi:[1,0]
	v_pk_mul_f32 v[182:183], v[10:11], v[146:147] op_sel_hi:[1,0]
	v_mul_f32_e32 v146, v0, v0
	v_pk_mul_f32 v[182:183], v[174:175], v[182:183]
	v_pk_mul_f32 v[174:175], v[172:173], v[180:181]
	v_cvt_pk_bf16_f32 v172, v176, v177
	v_cvt_pk_bf16_f32 v173, v178, v179
	v_cvt_pk_bf16_f32 v174, v174, v175
	v_cvt_pk_bf16_f32 v175, v182, v183
	global_store_dwordx4 v[148:149], v[172:175], off offset:64
	v_pk_mul_f32 v[148:149], v[22:23], v[22:23]
	s_nop 0
	v_pk_mul_f32 v[172:173], v[20:21], v[20:21]
	s_nop 0
	v_pk_mov_b32 v[174:175], v[172:173], v[148:149] op_sel:[1,0]
	v_mov_b32_e32 v173, v149
	v_pk_add_f32 v[148:149], v[174:175], v[172:173]
	v_pk_mul_f32 v[172:173], v[18:19], v[18:19]
	v_pk_mul_f32 v[174:175], v[16:17], v[16:17]
	v_pk_add_f32 v[148:149], v[148:149], v[148:149] op_sel:[0,1] op_sel_hi:[1,0]
	v_pk_mov_b32 v[176:177], v[174:175], v[172:173] op_sel:[1,0]
	v_mov_b32_e32 v175, v173
	v_pk_add_f32 v[172:173], v[176:177], v[174:175]
	v_mov_b32_e32 v149, v146
	v_pk_add_f32 v[172:173], v[172:173], v[172:173] op_sel:[0,1] op_sel_hi:[1,0]
	v_mul_f32_e32 v146, v5, v5
	v_mov_b32_e32 v173, v171
	v_mul_f32_e32 v174, v2, v2
	v_pk_add_f32 v[148:149], v[148:149], v[172:173]
	v_pk_fma_f32 v[172:173], v[4:5], v[4:5], v[146:147] op_sel_hi:[1,1,0]
	v_mul_f32_e32 v146, v7, v7
	v_mul_f32_e32 v176, v3, v3
	v_mov_b32_e32 v173, v174
	v_pk_fma_f32 v[174:175], v[6:7], v[6:7], v[146:147] op_sel_hi:[1,1,0]
	s_nop 0
	v_mov_b32_e32 v175, v176
	v_pk_add_f32 v[172:173], v[172:173], v[174:175]
	s_nop 0
	v_pk_add_f32 v[148:149], v[148:149], v[172:173]
	s_nop 0
	v_add_f32_e32 v146, v148, v149
	ds_bpermute_b32 v149, v153, v146
	v_add_u32_e32 v148, s11, v161
	s_waitcnt lgkmcnt(0)
	v_add_f32_e32 v146, v146, v149
	ds_bpermute_b32 v149, v154, v146
	s_waitcnt lgkmcnt(0)
	v_add_f32_e32 v146, v146, v149
	v_fmamk_f32 v146, v146, 0x3c800000, v168
	v_rsq_f32_e32 v146, v146
	v_ashrrev_i32_e32 v149, 31, v148
	v_lshlrev_b64 v[148:149], 11, v[148:149]
	v_lshl_add_u64 v[148:149], s[36:37], 0, v[148:149]
	v_mul_f32_e32 v146, v170, v146
	s_nop 1
	v_mov_b64_e32 v[170:171], v[252:253]
	v_mov_b64_e32 v[172:173], v[254:255]
	v_mov_b64_e32 v[174:175], v[248:249]
	v_mov_b64_e32 v[176:177], v[250:251]
	v_pk_mul_f32 v[178:179], v[20:21], v[146:147] op_sel_hi:[1,0]
	v_pk_mul_f32 v[180:181], v[22:23], v[146:147] op_sel_hi:[1,0]
	v_lshl_add_u64 v[148:149], v[148:149], 0, v[136:137]
	v_pk_mul_f32 v[176:177], v[176:177], v[180:181]
	v_pk_mul_f32 v[174:175], v[174:175], v[178:179]
	v_pk_mul_f32 v[178:179], v[16:17], v[146:147] op_sel_hi:[1,0]
	v_pk_mul_f32 v[180:181], v[18:19], v[146:147] op_sel_hi:[1,0]
	s_nop 0
	v_pk_mul_f32 v[180:181], v[172:173], v[180:181]
	v_pk_mul_f32 v[172:173], v[170:171], v[178:179]
	v_cvt_pk_bf16_f32 v170, v174, v175
	v_cvt_pk_bf16_f32 v171, v176, v177
	v_cvt_pk_bf16_f32 v172, v172, v173
	v_cvt_pk_bf16_f32 v173, v180, v181
	global_store_dwordx4 v[148:149], v[170:173], off
	s_nop 1
	v_mov_b64_e32 v[170:171], v[124:125]
	v_mov_b64_e32 v[172:173], v[126:127]
	s_nop 0
	v_mov_b64_e32 v[174:175], v[120:121]
	v_mov_b64_e32 v[176:177], v[122:123]
	v_pk_mul_f32 v[178:179], v[4:5], v[146:147] op_sel_hi:[1,0]
	v_pk_mul_f32 v[180:181], v[6:7], v[146:147] op_sel_hi:[1,0]
	v_pk_mul_f32 v[176:177], v[176:177], v[180:181]
	v_pk_mul_f32 v[174:175], v[174:175], v[178:179]
	v_pk_mul_f32 v[178:179], v[0:1], v[146:147] op_sel_hi:[1,0]
	v_pk_mul_f32 v[180:181], v[2:3], v[146:147] op_sel_hi:[1,0]
	s_nop 0
	v_pk_mul_f32 v[180:181], v[172:173], v[180:181]
	v_pk_mul_f32 v[172:173], v[170:171], v[178:179]
	v_cvt_pk_bf16_f32 v170, v174, v175
	v_cvt_pk_bf16_f32 v171, v176, v177
	v_cvt_pk_bf16_f32 v172, v172, v173
	v_cvt_pk_bf16_f32 v173, v180, v181
	global_store_dwordx4 v[148:149], v[170:173], off offset:64
	s_cbranch_execnz .LBB0_659

.LBB0_888:
	v_lshl_add_u32 v141, s26, 8, v144
	v_lshl_or_b32 v142, s4, 8, v146
	v_lshl_add_u32 v161, v141, 10, v142
	v_lshlrev_b32_e32 v160, 2, v161
	v_lshlrev_b32_e32 v161, 1, v161
	s_lshl_b32 s27, s4, 2
	s_add_i32 s27, s27, s44
	s_lshl_b32 s27, s27, 2
	v_lshlrev_b32_e32 v143, 6, v141
	v_add_u32_e32 v143, s27, v143
	global_load_dwordx4 v[152:155], v160, s[76:77]
	global_load_dwordx4 v[156:159], v160, s[76:77] offset:64
	s_waitcnt vmcnt(1)
	v_pk_add_f32 v[124:125], v[124:125], v[152:153]
	v_pk_add_f32 v[126:127], v[126:127], v[154:155]
	global_load_dwordx4 v[152:155], v160, s[76:77] offset:512
	v_mul_f32_e32 v141, v125, v125
	v_fmac_f32_e32 v141, v124, v124
	v_mul_f32_e32 v142, v127, v127
	v_fmac_f32_e32 v142, v126, v126
	v_add_f32_e32 v140, v141, v142
	v_cvt_pk_bf16_f32 v124, v124, v125
	v_cvt_pk_bf16_f32 v125, v126, v127
	global_store_dwordx2 v161, v[124:125], s[82:83]
	global_load_dwordx4 v[124:127], v160, s[76:77] offset:576
	v_add_u32_e32 v160, 0x10000, v160
	s_waitcnt vmcnt(3)
	v_pk_add_f32 v[120:121], v[120:121], v[156:157]
	v_pk_add_f32 v[122:123], v[122:123], v[158:159]
	global_load_dwordx4 v[156:159], v160, s[76:77]
	v_mul_f32_e32 v141, v121, v121
	v_fmac_f32_e32 v141, v120, v120
	v_mul_f32_e32 v142, v123, v123
	v_fmac_f32_e32 v142, v122, v122
	v_add_f32_e32 v141, v141, v142
	v_add_f32_e32 v140, v140, v141
	v_cvt_pk_bf16_f32 v120, v120, v121
	v_cvt_pk_bf16_f32 v121, v122, v123
	global_store_dwordx2 v161, v[120:121], s[82:83] offset:32
	global_load_dwordx4 v[120:123], v160, s[76:77] offset:64
	s_waitcnt vmcnt(5)
	v_pk_add_f32 v[116:117], v[116:117], v[152:153]
	v_pk_add_f32 v[118:119], v[118:119], v[154:155]
	global_load_dwordx4 v[152:155], v160, s[76:77] offset:512
	v_mul_f32_e32 v141, v117, v117
	v_fmac_f32_e32 v141, v116, v116
	v_mul_f32_e32 v142, v119, v119
	v_fmac_f32_e32 v142, v118, v118
	v_add_f32_e32 v141, v141, v142
	v_add_f32_e32 v140, v140, v141
	v_cvt_pk_bf16_f32 v116, v116, v117
	v_cvt_pk_bf16_f32 v117, v118, v119
	global_store_dwordx2 v161, v[116:117], s[82:83] offset:256
	global_load_dwordx4 v[116:119], v160, s[76:77] offset:576
	v_add_u32_e32 v160, 0x10000, v160
	s_waitcnt vmcnt(6)
	v_pk_add_f32 v[112:113], v[112:113], v[124:125]
	v_pk_add_f32 v[114:115], v[114:115], v[126:127]
	global_load_dwordx4 v[124:127], v160, s[76:77]
	v_mul_f32_e32 v141, v113, v113
	v_fmac_f32_e32 v141, v112, v112
	v_mul_f32_e32 v142, v115, v115
	v_fmac_f32_e32 v142, v114, v114
	v_add_f32_e32 v141, v141, v142
	v_add_f32_e32 v140, v140, v141
	v_cvt_pk_bf16_f32 v112, v112, v113
	v_cvt_pk_bf16_f32 v113, v114, v115
	global_store_dwordx2 v161, v[112:113], s[82:83] offset:288
	global_load_dwordx4 v[112:115], v160, s[76:77] offset:64
	v_add_u32_e32 v161, 0x8000, v161
	ds_bpermute_b32 v141, v147, v140
	s_waitcnt lgkmcnt(0)
	v_add_f32_e32 v140, v140, v141
	ds_bpermute_b32 v141, v148, v140
	s_waitcnt lgkmcnt(0)
	v_add_f32_e32 v140, v140, v141
	s_and_saveexec_b64 s[30:31], s[40:41]
	global_store_dword v143, v140, s[22:23]
	s_or_b64 exec, exec, s[30:31]
	v_add_u32_e32 v143, 0x400, v143
	s_waitcnt vmcnt(9)
	v_pk_add_f32 v[108:109], v[108:109], v[156:157]
	v_pk_add_f32 v[110:111], v[110:111], v[158:159]
	global_load_dwordx4 v[156:159], v160, s[76:77] offset:512
	v_mul_f32_e32 v141, v109, v109
	v_fmac_f32_e32 v141, v108, v108
	v_mul_f32_e32 v142, v111, v111
	v_fmac_f32_e32 v142, v110, v110
	v_add_f32_e32 v140, v141, v142
	v_cvt_pk_bf16_f32 v108, v108, v109
	v_cvt_pk_bf16_f32 v109, v110, v111
	global_store_dwordx2 v161, v[108:109], s[82:83]
	global_load_dwordx4 v[108:111], v160, s[76:77] offset:576
	v_add_u32_e32 v160, 0x10000, v160
	s_waitcnt vmcnt(10)
	v_pk_add_f32 v[104:105], v[104:105], v[120:121]
	v_pk_add_f32 v[106:107], v[106:107], v[122:123]
	global_load_dwordx4 v[120:123], v160, s[76:77]
	v_mul_f32_e32 v141, v105, v105
	v_fmac_f32_e32 v141, v104, v104
	v_mul_f32_e32 v142, v107, v107
	v_fmac_f32_e32 v142, v106, v106
	v_add_f32_e32 v141, v141, v142
	v_add_f32_e32 v140, v140, v141
	v_cvt_pk_bf16_f32 v104, v104, v105
	v_cvt_pk_bf16_f32 v105, v106, v107
	global_store_dwordx2 v161, v[104:105], s[82:83] offset:32
	global_load_dwordx4 v[104:107], v160, s[76:77] offset:64
	s_waitcnt vmcnt(12)
	v_pk_add_f32 v[100:101], v[100:101], v[152:153]
	v_pk_add_f32 v[102:103], v[102:103], v[154:155]
	global_load_dwordx4 v[152:155], v160, s[76:77] offset:512
	v_mul_f32_e32 v141, v101, v101
	v_fmac_f32_e32 v141, v100, v100
	v_mul_f32_e32 v142, v103, v103
	v_fmac_f32_e32 v142, v102, v102
	v_add_f32_e32 v141, v141, v142
	v_add_f32_e32 v140, v140, v141
	v_cvt_pk_bf16_f32 v100, v100, v101
	v_cvt_pk_bf16_f32 v101, v102, v103
	global_store_dwordx2 v161, v[100:101], s[82:83] offset:256
	global_load_dwordx4 v[100:103], v160, s[76:77] offset:576
	v_add_u32_e32 v160, 0x50000, v160
	s_waitcnt vmcnt(13)
	v_pk_add_f32 v[96:97], v[96:97], v[116:117]
	v_pk_add_f32 v[98:99], v[98:99], v[118:119]
	global_load_dwordx4 v[116:119], v160, s[76:77]
	v_mul_f32_e32 v141, v97, v97
	v_fmac_f32_e32 v141, v96, v96
	v_mul_f32_e32 v142, v99, v99
	v_fmac_f32_e32 v142, v98, v98
	v_add_f32_e32 v141, v141, v142
	v_add_f32_e32 v140, v140, v141
	v_cvt_pk_bf16_f32 v96, v96, v97
	v_cvt_pk_bf16_f32 v97, v98, v99
	global_store_dwordx2 v161, v[96:97], s[82:83] offset:288
	global_load_dwordx4 v[96:99], v160, s[76:77] offset:64
	v_add_u32_e32 v161, 0x8000, v161
	ds_bpermute_b32 v141, v147, v140
	s_waitcnt lgkmcnt(0)
	v_add_f32_e32 v140, v140, v141
	ds_bpermute_b32 v141, v148, v140
	s_waitcnt lgkmcnt(0)
	v_add_f32_e32 v140, v140, v141
	s_and_saveexec_b64 s[30:31], s[40:41]
	global_store_dword v143, v140, s[22:23]
	s_or_b64 exec, exec, s[30:31]
	v_add_u32_e32 v143, 0x400, v143
	s_waitcnt vmcnt(16)
	v_pk_add_f32 v[92:93], v[92:93], v[124:125]
	v_pk_add_f32 v[94:95], v[94:95], v[126:127]
	global_load_dwordx4 v[124:127], v160, s[76:77] offset:512
	v_mul_f32_e32 v141, v93, v93
	v_fmac_f32_e32 v141, v92, v92
	v_mul_f32_e32 v142, v95, v95
	v_fmac_f32_e32 v142, v94, v94
	v_add_f32_e32 v140, v141, v142
	v_cvt_pk_bf16_f32 v92, v92, v93
	v_cvt_pk_bf16_f32 v93, v94, v95
	global_store_dwordx2 v161, v[92:93], s[82:83]
	global_load_dwordx4 v[92:95], v160, s[76:77] offset:576
	v_add_u32_e32 v160, 0x10000, v160
	s_waitcnt vmcnt(17)
	v_pk_add_f32 v[88:89], v[88:89], v[112:113]
	v_pk_add_f32 v[90:91], v[90:91], v[114:115]
	global_load_dwordx4 v[112:115], v160, s[76:77]
	v_mul_f32_e32 v141, v89, v89
	v_fmac_f32_e32 v141, v88, v88
	v_mul_f32_e32 v142, v91, v91
	v_fmac_f32_e32 v142, v90, v90
	v_add_f32_e32 v141, v141, v142
	v_add_f32_e32 v140, v140, v141
	v_cvt_pk_bf16_f32 v88, v88, v89
	v_cvt_pk_bf16_f32 v89, v90, v91
	global_store_dwordx2 v161, v[88:89], s[82:83] offset:32
	global_load_dwordx4 v[88:91], v160, s[76:77] offset:64
	s_waitcnt vmcnt(18)
	v_pk_add_f32 v[84:85], v[84:85], v[156:157]
	v_pk_add_f32 v[86:87], v[86:87], v[158:159]
	global_load_dwordx4 v[156:159], v160, s[76:77] offset:512
	v_mul_f32_e32 v141, v85, v85
	v_fmac_f32_e32 v141, v84, v84
	v_mul_f32_e32 v142, v87, v87
	v_fmac_f32_e32 v142, v86, v86
	v_add_f32_e32 v141, v141, v142
	v_add_f32_e32 v140, v140, v141
	v_cvt_pk_bf16_f32 v84, v84, v85
	v_cvt_pk_bf16_f32 v85, v86, v87
	global_store_dwordx2 v161, v[84:85], s[82:83] offset:256
	global_load_dwordx4 v[84:87], v160, s[76:77] offset:576
	v_add_u32_e32 v160, 0x10000, v160
	s_waitcnt vmcnt(19)
	v_pk_add_f32 v[80:81], v[80:81], v[108:109]
	v_pk_add_f32 v[82:83], v[82:83], v[110:111]
	global_load_dwordx4 v[108:111], v160, s[76:77]
	v_mul_f32_e32 v141, v81, v81
	v_fmac_f32_e32 v141, v80, v80
	v_mul_f32_e32 v142, v83, v83
	v_fmac_f32_e32 v142, v82, v82
	v_add_f32_e32 v141, v141, v142
	v_add_f32_e32 v140, v140, v141
	v_cvt_pk_bf16_f32 v80, v80, v81
	v_cvt_pk_bf16_f32 v81, v82, v83
	global_store_dwordx2 v161, v[80:81], s[82:83] offset:288
	global_load_dwordx4 v[80:83], v160, s[76:77] offset:64
	v_add_u32_e32 v161, 0x8000, v161
	ds_bpermute_b32 v141, v147, v140
	s_waitcnt lgkmcnt(0)
	v_add_f32_e32 v140, v140, v141
	ds_bpermute_b32 v141, v148, v140
	s_waitcnt lgkmcnt(0)
	v_add_f32_e32 v140, v140, v141
	s_and_saveexec_b64 s[30:31], s[40:41]
	global_store_dword v143, v140, s[22:23]
	s_or_b64 exec, exec, s[30:31]
	v_add_u32_e32 v143, 0x400, v143
	s_waitcnt vmcnt(22)
	v_pk_add_f32 v[76:77], v[76:77], v[120:121]
	v_pk_add_f32 v[78:79], v[78:79], v[122:123]
	global_load_dwordx4 v[120:123], v160, s[76:77] offset:512
	v_mul_f32_e32 v141, v77, v77
	v_fmac_f32_e32 v141, v76, v76
	v_mul_f32_e32 v142, v79, v79
	v_fmac_f32_e32 v142, v78, v78
	v_add_f32_e32 v140, v141, v142
	v_cvt_pk_bf16_f32 v76, v76, v77
	v_cvt_pk_bf16_f32 v77, v78, v79
	global_store_dwordx2 v161, v[76:77], s[82:83]
	global_load_dwordx4 v[76:79], v160, s[76:77] offset:576
	v_add_u32_e32 v160, 0x10000, v160
	s_waitcnt vmcnt(23)
	v_pk_add_f32 v[72:73], v[72:73], v[104:105]
	v_pk_add_f32 v[74:75], v[74:75], v[106:107]
	global_load_dwordx4 v[104:107], v160, s[76:77]
	v_mul_f32_e32 v141, v73, v73
	v_fmac_f32_e32 v141, v72, v72
	v_mul_f32_e32 v142, v75, v75
	v_fmac_f32_e32 v142, v74, v74
	v_add_f32_e32 v141, v141, v142
	v_add_f32_e32 v140, v140, v141
	v_cvt_pk_bf16_f32 v72, v72, v73
	v_cvt_pk_bf16_f32 v73, v74, v75
	global_store_dwordx2 v161, v[72:73], s[82:83] offset:32
	global_load_dwordx4 v[72:75], v160, s[76:77] offset:64
	s_waitcnt vmcnt(25)
	v_pk_add_f32 v[68:69], v[68:69], v[152:153]
	v_pk_add_f32 v[70:71], v[70:71], v[154:155]
	global_load_dwordx4 v[152:155], v160, s[76:77] offset:512
	v_mul_f32_e32 v141, v69, v69
	v_fmac_f32_e32 v141, v68, v68
	v_mul_f32_e32 v142, v71, v71
	v_fmac_f32_e32 v142, v70, v70
	v_add_f32_e32 v141, v141, v142
	v_add_f32_e32 v140, v140, v141
	v_cvt_pk_bf16_f32 v68, v68, v69
	v_cvt_pk_bf16_f32 v69, v70, v71
	global_store_dwordx2 v161, v[68:69], s[82:83] offset:256
	global_load_dwordx4 v[68:71], v160, s[76:77] offset:576
	s_waitcnt vmcnt(26)
	v_pk_add_f32 v[64:65], v[64:65], v[100:101]
	v_pk_add_f32 v[66:67], v[66:67], v[102:103]
	v_mul_f32_e32 v141, v65, v65
	v_fmac_f32_e32 v141, v64, v64
	v_mul_f32_e32 v142, v67, v67
	v_fmac_f32_e32 v142, v66, v66
	v_add_f32_e32 v141, v141, v142
	v_add_f32_e32 v140, v140, v141
	v_cvt_pk_bf16_f32 v64, v64, v65
	v_cvt_pk_bf16_f32 v65, v66, v67
	global_store_dwordx2 v161, v[64:65], s[82:83] offset:288
	v_add_u32_e32 v161, 0x28000, v161
	ds_bpermute_b32 v141, v147, v140
	s_waitcnt lgkmcnt(0)
	v_add_f32_e32 v140, v140, v141
	ds_bpermute_b32 v141, v148, v140
	s_waitcnt lgkmcnt(0)
	v_add_f32_e32 v140, v140, v141
	s_and_saveexec_b64 s[30:31], s[40:41]
	global_store_dword v143, v140, s[22:23]
	s_or_b64 exec, exec, s[30:31]
	v_add_u32_e32 v143, 0x1400, v143
	s_waitcnt vmcnt(27)
	v_pk_add_f32 v[60:61], v[60:61], v[116:117]
	v_pk_add_f32 v[62:63], v[62:63], v[118:119]
	v_mul_f32_e32 v141, v61, v61
	v_fmac_f32_e32 v141, v60, v60
	v_mul_f32_e32 v142, v63, v63
	v_fmac_f32_e32 v142, v62, v62
	v_add_f32_e32 v140, v141, v142
	v_cvt_pk_bf16_f32 v60, v60, v61
	v_cvt_pk_bf16_f32 v61, v62, v63
	global_store_dwordx2 v161, v[60:61], s[82:83]
	s_waitcnt vmcnt(26)
	v_pk_add_f32 v[56:57], v[56:57], v[96:97]
	v_pk_add_f32 v[58:59], v[58:59], v[98:99]
	v_mul_f32_e32 v141, v57, v57
	v_fmac_f32_e32 v141, v56, v56
	v_mul_f32_e32 v142, v59, v59
	v_fmac_f32_e32 v142, v58, v58
	v_add_f32_e32 v141, v141, v142
	v_add_f32_e32 v140, v140, v141
	v_cvt_pk_bf16_f32 v56, v56, v57
	v_cvt_pk_bf16_f32 v57, v58, v59
	global_store_dwordx2 v161, v[56:57], s[82:83] offset:32
	s_waitcnt vmcnt(25)
	v_pk_add_f32 v[52:53], v[52:53], v[124:125]
	v_pk_add_f32 v[54:55], v[54:55], v[126:127]
	v_mul_f32_e32 v141, v53, v53
	v_fmac_f32_e32 v141, v52, v52
	v_mul_f32_e32 v142, v55, v55
	v_fmac_f32_e32 v142, v54, v54
	v_add_f32_e32 v141, v141, v142
	v_add_f32_e32 v140, v140, v141
	v_cvt_pk_bf16_f32 v52, v52, v53
	v_cvt_pk_bf16_f32 v53, v54, v55
	global_store_dwordx2 v161, v[52:53], s[82:83] offset:256
	s_waitcnt vmcnt(24)
	v_pk_add_f32 v[48:49], v[48:49], v[92:93]
	v_pk_add_f32 v[50:51], v[50:51], v[94:95]
	v_mul_f32_e32 v141, v49, v49
	v_fmac_f32_e32 v141, v48, v48
	v_mul_f32_e32 v142, v51, v51
	v_fmac_f32_e32 v142, v50, v50
	v_add_f32_e32 v141, v141, v142
	v_add_f32_e32 v140, v140, v141
	v_cvt_pk_bf16_f32 v48, v48, v49
	v_cvt_pk_bf16_f32 v49, v50, v51
	global_store_dwordx2 v161, v[48:49], s[82:83] offset:288
	v_add_u32_e32 v161, 0x8000, v161
	ds_bpermute_b32 v141, v147, v140
	s_waitcnt lgkmcnt(0)
	v_add_f32_e32 v140, v140, v141
	ds_bpermute_b32 v141, v148, v140
	s_waitcnt lgkmcnt(0)
	v_add_f32_e32 v140, v140, v141
	s_and_saveexec_b64 s[30:31], s[40:41]
	global_store_dword v143, v140, s[22:23]
	s_or_b64 exec, exec, s[30:31]
	v_add_u32_e32 v143, 0x400, v143
	s_waitcnt vmcnt(25)
	v_pk_add_f32 v[44:45], v[44:45], v[112:113]
	v_pk_add_f32 v[46:47], v[46:47], v[114:115]
	v_mul_f32_e32 v141, v45, v45
	v_fmac_f32_e32 v141, v44, v44
	v_mul_f32_e32 v142, v47, v47
	v_fmac_f32_e32 v142, v46, v46
	v_add_f32_e32 v140, v141, v142
	v_cvt_pk_bf16_f32 v44, v44, v45
	v_cvt_pk_bf16_f32 v45, v46, v47
	global_store_dwordx2 v161, v[44:45], s[82:83]
	s_waitcnt vmcnt(24)
	v_pk_add_f32 v[40:41], v[40:41], v[88:89]
	v_pk_add_f32 v[42:43], v[42:43], v[90:91]
	v_mul_f32_e32 v141, v41, v41
	v_fmac_f32_e32 v141, v40, v40
	v_mul_f32_e32 v142, v43, v43
	v_fmac_f32_e32 v142, v42, v42
	v_add_f32_e32 v141, v141, v142
	v_add_f32_e32 v140, v140, v141
	v_cvt_pk_bf16_f32 v40, v40, v41
	v_cvt_pk_bf16_f32 v41, v42, v43
	global_store_dwordx2 v161, v[40:41], s[82:83] offset:32
	s_waitcnt vmcnt(24)
	v_pk_add_f32 v[36:37], v[36:37], v[156:157]
	v_pk_add_f32 v[38:39], v[38:39], v[158:159]
	v_mul_f32_e32 v141, v37, v37
	v_fmac_f32_e32 v141, v36, v36
	v_mul_f32_e32 v142, v39, v39
	v_fmac_f32_e32 v142, v38, v38
	v_add_f32_e32 v141, v141, v142
	v_add_f32_e32 v140, v140, v141
	v_cvt_pk_bf16_f32 v36, v36, v37
	v_cvt_pk_bf16_f32 v37, v38, v39
	global_store_dwordx2 v161, v[36:37], s[82:83] offset:256
	s_waitcnt vmcnt(23)
	v_pk_add_f32 v[32:33], v[32:33], v[84:85]
	v_pk_add_f32 v[34:35], v[34:35], v[86:87]
	v_mul_f32_e32 v141, v33, v33
	v_fmac_f32_e32 v141, v32, v32
	v_mul_f32_e32 v142, v35, v35
	v_fmac_f32_e32 v142, v34, v34
	v_add_f32_e32 v141, v141, v142
	v_add_f32_e32 v140, v140, v141
	v_cvt_pk_bf16_f32 v32, v32, v33
	v_cvt_pk_bf16_f32 v33, v34, v35
	global_store_dwordx2 v161, v[32:33], s[82:83] offset:288
	v_add_u32_e32 v161, 0x8000, v161
	ds_bpermute_b32 v141, v147, v140
	s_waitcnt lgkmcnt(0)
	v_add_f32_e32 v140, v140, v141
	ds_bpermute_b32 v141, v148, v140
	s_waitcnt lgkmcnt(0)
	v_add_f32_e32 v140, v140, v141
	s_and_saveexec_b64 s[30:31], s[40:41]
	global_store_dword v143, v140, s[22:23]
	s_or_b64 exec, exec, s[30:31]
	v_add_u32_e32 v143, 0x400, v143
	s_waitcnt vmcnt(24)
	v_pk_add_f32 v[28:29], v[28:29], v[108:109]
	v_pk_add_f32 v[30:31], v[30:31], v[110:111]
	v_mul_f32_e32 v141, v29, v29
	v_fmac_f32_e32 v141, v28, v28
	v_mul_f32_e32 v142, v31, v31
	v_fmac_f32_e32 v142, v30, v30
	v_add_f32_e32 v140, v141, v142
	v_cvt_pk_bf16_f32 v28, v28, v29
	v_cvt_pk_bf16_f32 v29, v30, v31
	global_store_dwordx2 v161, v[28:29], s[82:83]
	s_waitcnt vmcnt(23)
	v_pk_add_f32 v[24:25], v[24:25], v[80:81]
	v_pk_add_f32 v[26:27], v[26:27], v[82:83]
	v_mul_f32_e32 v141, v25, v25
	v_fmac_f32_e32 v141, v24, v24
	v_mul_f32_e32 v142, v27, v27
	v_fmac_f32_e32 v142, v26, v26
	v_add_f32_e32 v141, v141, v142
	v_add_f32_e32 v140, v140, v141
	v_cvt_pk_bf16_f32 v24, v24, v25
	v_cvt_pk_bf16_f32 v25, v26, v27
	global_store_dwordx2 v161, v[24:25], s[82:83] offset:32
	s_waitcnt vmcnt(22)
	v_pk_add_f32 v[20:21], v[20:21], v[120:121]
	v_pk_add_f32 v[22:23], v[22:23], v[122:123]
	v_mul_f32_e32 v141, v21, v21
	v_fmac_f32_e32 v141, v20, v20
	v_mul_f32_e32 v142, v23, v23
	v_fmac_f32_e32 v142, v22, v22
	v_add_f32_e32 v141, v141, v142
	v_add_f32_e32 v140, v140, v141
	v_cvt_pk_bf16_f32 v20, v20, v21
	v_cvt_pk_bf16_f32 v21, v22, v23
	global_store_dwordx2 v161, v[20:21], s[82:83] offset:256
	s_waitcnt vmcnt(21)
	v_pk_add_f32 v[16:17], v[16:17], v[76:77]
	v_pk_add_f32 v[18:19], v[18:19], v[78:79]
	v_mul_f32_e32 v141, v17, v17
	v_fmac_f32_e32 v141, v16, v16
	v_mul_f32_e32 v142, v19, v19
	v_fmac_f32_e32 v142, v18, v18
	v_add_f32_e32 v141, v141, v142
	v_add_f32_e32 v140, v140, v141
	v_cvt_pk_bf16_f32 v16, v16, v17
	v_cvt_pk_bf16_f32 v17, v18, v19
	global_store_dwordx2 v161, v[16:17], s[82:83] offset:288
	v_add_u32_e32 v161, 0x8000, v161
	ds_bpermute_b32 v141, v147, v140
	s_waitcnt lgkmcnt(0)
	v_add_f32_e32 v140, v140, v141
	ds_bpermute_b32 v141, v148, v140
	s_waitcnt lgkmcnt(0)
	v_add_f32_e32 v140, v140, v141
	s_and_saveexec_b64 s[30:31], s[40:41]
	global_store_dword v143, v140, s[22:23]
	s_or_b64 exec, exec, s[30:31]
	v_add_u32_e32 v143, 0x400, v143
	s_waitcnt vmcnt(22)
	v_pk_add_f32 v[12:13], v[12:13], v[104:105]
	v_pk_add_f32 v[14:15], v[14:15], v[106:107]
	v_mul_f32_e32 v141, v13, v13
	v_fmac_f32_e32 v141, v12, v12
	v_mul_f32_e32 v142, v15, v15
	v_fmac_f32_e32 v142, v14, v14
	v_add_f32_e32 v140, v141, v142
	v_cvt_pk_bf16_f32 v12, v12, v13
	v_cvt_pk_bf16_f32 v13, v14, v15
	global_store_dwordx2 v161, v[12:13], s[82:83]
	s_waitcnt vmcnt(21)
	v_pk_add_f32 v[8:9], v[8:9], v[72:73]
	v_pk_add_f32 v[10:11], v[10:11], v[74:75]
	v_mul_f32_e32 v141, v9, v9
	v_fmac_f32_e32 v141, v8, v8
	v_mul_f32_e32 v142, v11, v11
	v_fmac_f32_e32 v142, v10, v10
	v_add_f32_e32 v141, v141, v142
	v_add_f32_e32 v140, v140, v141
	v_cvt_pk_bf16_f32 v8, v8, v9
	v_cvt_pk_bf16_f32 v9, v10, v11
	global_store_dwordx2 v161, v[8:9], s[82:83] offset:32
	s_waitcnt vmcnt(21)
	v_pk_add_f32 v[4:5], v[4:5], v[152:153]
	v_pk_add_f32 v[6:7], v[6:7], v[154:155]
	v_mul_f32_e32 v141, v5, v5
	v_fmac_f32_e32 v141, v4, v4
	v_mul_f32_e32 v142, v7, v7
	v_fmac_f32_e32 v142, v6, v6
	v_add_f32_e32 v141, v141, v142
	v_add_f32_e32 v140, v140, v141
	v_cvt_pk_bf16_f32 v4, v4, v5
	v_cvt_pk_bf16_f32 v5, v6, v7
	global_store_dwordx2 v161, v[4:5], s[82:83] offset:256
	s_waitcnt vmcnt(20)
	v_pk_add_f32 v[0:1], v[0:1], v[68:69]
	v_pk_add_f32 v[2:3], v[2:3], v[70:71]
	v_mul_f32_e32 v141, v1, v1
	v_fmac_f32_e32 v141, v0, v0
	v_mul_f32_e32 v142, v3, v3
	v_fmac_f32_e32 v142, v2, v2
	v_add_f32_e32 v141, v141, v142
	v_add_f32_e32 v140, v140, v141
	v_cvt_pk_bf16_f32 v0, v0, v1
	v_cvt_pk_bf16_f32 v1, v2, v3
	global_store_dwordx2 v161, v[0:1], s[82:83] offset:288
	ds_bpermute_b32 v141, v147, v140
	s_waitcnt lgkmcnt(0)
	v_add_f32_e32 v140, v140, v141
	ds_bpermute_b32 v141, v148, v140
	s_waitcnt lgkmcnt(0)
	v_add_f32_e32 v140, v140, v141
	s_and_saveexec_b64 s[30:31], s[40:41]
	global_store_dword v143, v140, s[22:23]
